# FFN1 round 6 shared by block pairs as 128-token half tiles: half loop now also skips the unused token-half ds_reads and LDS-DMA loads (vmcnt 6)
# speedup vs baseline: 1.0084x; 1.0084x over previous
.Lhalf511:
	s_add_i32 s62, s30, 2
	s_add_u32 s63, s28, 0x80
	s_addc_u32 s31, s29, 0
	s_add_i32 s66, 0, 0x10000
	s_cmp_eq_u32 s54, s30
	s_cselect_b32 s31, s7, s31
	s_cselect_b32 s30, s6, s63
	v_add_u32_e32 v156, s66, v141
	s_cselect_b32 s65, s27, s61
	s_cselect_b32 s64, s26, s60
	s_add_i32 s63, 0, 0x14000
	ds_read_b128 v[144:147], v156
	ds_read_b128 v[148:151], v156 offset:1024
	ds_read_b128 v[152:155], v156 offset:2048
	ds_read_b128 v[160:163], v156 offset:3072
	v_add_u32_e32 v156, s63, v141
	ds_read_b128 v[164:167], v156
	ds_read_b128 v[168:171], v156 offset:1024
	ds_read_b128 v[172:175], v156 offset:2048
	ds_read_b128 v[176:179], v156 offset:3072
	v_lshl_add_u64 v[156:157], s[28:29], 0, v[136:137]
	s_add_i32 m0, s47, 0xc000
	s_cmp_eq_u32 s98, 2
	s_cbranch_scc1 .Lhr0
	ds_read_b128 v[180:183], v143
	ds_read_b128 v[184:187], v143 offset:1024
	ds_read_b128 v[188:191], v143 offset:2048
	ds_read_b128 v[192:195], v143 offset:3072
	ds_read_b128 v[214:217], v143 offset:4096
	ds_read_b128 v[218:221], v143 offset:5120
	ds_read_b128 v[222:225], v143 offset:6144
	ds_read_b128 v[226:229], v143 offset:7168
.Lhr0:
	s_cmp_eq_u32 s98, 1
	s_cbranch_scc1 .Lhd1
	global_load_lds_dwordx4 v[156:157], off
.Lhd1:
	v_lshl_add_u64 v[156:157], s[28:29], 0, v[138:139]
	s_add_i32 m0, s47, 0xe000
	s_nop 0
	s_cmp_eq_u32 s98, 1
	s_cbranch_scc1 .Lhd2
	global_load_lds_dwordx4 v[156:157], off
.Lhd2:
	s_waitcnt vmcnt(6)
	s_waitcnt lgkmcnt(0)
	s_barrier
	s_setprio 1
	s_waitcnt lgkmcnt(0)
	s_cmp_eq_u32 s98, 2
	s_cbranch_scc1 .Lhskip1
	v_mfma_f32_16x16x32_bf16 v[122:125], v[144:147], v[180:183], v[122:125]
	v_mfma_f32_16x16x32_bf16 v[118:121], v[152:155], v[180:183], v[118:121]
	v_mfma_f32_16x16x32_bf16 v[110:113], v[144:147], v[188:191], v[110:113]
	v_mfma_f32_16x16x32_bf16 v[102:105], v[152:155], v[188:191], v[102:105]
	v_mfma_f32_16x16x32_bf16 v[94:97], v[144:147], v[214:217], v[94:97]
	v_mfma_f32_16x16x32_bf16 v[84:87], v[152:155], v[214:217], v[84:87]
	v_mfma_f32_16x16x32_bf16 v[76:79], v[144:147], v[222:225], v[76:79]
	v_mfma_f32_16x16x32_bf16 v[68:71], v[152:155], v[222:225], v[68:71]
	v_mfma_f32_16x16x32_bf16 v[122:125], v[148:151], v[184:187], v[122:125]
	v_mfma_f32_16x16x32_bf16 v[118:121], v[160:163], v[184:187], v[118:121]
	v_mfma_f32_16x16x32_bf16 v[110:113], v[148:151], v[192:195], v[110:113]
	v_mfma_f32_16x16x32_bf16 v[102:105], v[160:163], v[192:195], v[102:105]
	v_mfma_f32_16x16x32_bf16 v[94:97], v[148:151], v[218:221], v[94:97]
	v_mfma_f32_16x16x32_bf16 v[84:87], v[160:163], v[218:221], v[84:87]
	v_mfma_f32_16x16x32_bf16 v[76:79], v[148:151], v[226:229], v[76:79]
	v_mfma_f32_16x16x32_bf16 v[68:71], v[160:163], v[226:229], v[68:71]
	s_setprio 0
	s_setprio 1
	v_mfma_f32_16x16x32_bf16 v[126:129], v[164:167], v[180:183], v[126:129]
	v_mfma_f32_16x16x32_bf16 v[114:117], v[172:175], v[180:183], v[114:117]
	v_mfma_f32_16x16x32_bf16 v[106:109], v[164:167], v[188:191], v[106:109]
	v_mfma_f32_16x16x32_bf16 v[98:101], v[172:175], v[188:191], v[98:101]
	v_mfma_f32_16x16x32_bf16 v[88:91], v[164:167], v[214:217], v[88:91]
	v_mfma_f32_16x16x32_bf16 v[80:83], v[172:175], v[214:217], v[80:83]
	v_mfma_f32_16x16x32_bf16 v[72:75], v[164:167], v[222:225], v[72:75]
	v_mfma_f32_16x16x32_bf16 v[64:67], v[172:175], v[222:225], v[64:67]
	v_mfma_f32_16x16x32_bf16 v[126:129], v[168:171], v[184:187], v[126:129]
	v_mfma_f32_16x16x32_bf16 v[114:117], v[176:179], v[184:187], v[114:117]
	v_mfma_f32_16x16x32_bf16 v[106:109], v[168:171], v[192:195], v[106:109]
	v_mfma_f32_16x16x32_bf16 v[98:101], v[176:179], v[192:195], v[98:101]
	v_mfma_f32_16x16x32_bf16 v[88:91], v[168:171], v[218:221], v[88:91]
	v_mfma_f32_16x16x32_bf16 v[80:83], v[176:179], v[218:221], v[80:83]
	v_mfma_f32_16x16x32_bf16 v[72:75], v[168:171], v[226:229], v[72:75]
	v_mfma_f32_16x16x32_bf16 v[64:67], v[176:179], v[226:229], v[64:67]
.Lhskip1:
	s_setprio 0
	s_barrier
	s_add_i32 s66, s66, s44
	v_lshl_add_u64 v[156:157], s[64:65], 0, v[92:93]
	s_mov_b32 m0, s66
	s_cmp_eq_u32 s98, 1
	s_cbranch_scc1 .Lhr3
	ds_read_b128 v[180:183], v143 offset:16384
	ds_read_b128 v[184:187], v143 offset:17408
	ds_read_b128 v[188:191], v143 offset:18432
	ds_read_b128 v[192:195], v143 offset:19456
	ds_read_b128 v[214:217], v143 offset:20480
	ds_read_b128 v[218:221], v143 offset:21504
	ds_read_b128 v[222:225], v143 offset:22528
	ds_read_b128 v[226:229], v143 offset:23552
.Lhr3:
	global_load_lds_dwordx4 v[156:157], off
	s_add_i32 m0, s66, 0x2000
	v_lshl_add_u64 v[230:231], s[64:65], 0, v[134:135]
	s_add_u32 s64, s64, s10
	s_addc_u32 s65, s65, s11
	s_add_i32 s63, s63, s44
	global_load_lds_dwordx4 v[230:231], off
	v_lshl_add_u64 v[232:233], s[64:65], 0, v[92:93]
	s_mov_b32 m0, s63
	v_lshl_add_u64 v[234:235], s[64:65], 0, v[134:135]
	global_load_lds_dwordx4 v[232:233], off
	s_add_i32 m0, s63, 0x2000
	v_lshl_add_u64 v[236:237], s[30:31], 0, v[130:131]
	global_load_lds_dwordx4 v[234:235], off
	s_mov_b32 m0, s47
	v_lshl_add_u64 v[238:239], s[30:31], 0, v[132:133]
	s_cmp_eq_u32 s98, 2
	s_cbranch_scc1 .Lhd4
	global_load_lds_dwordx4 v[236:237], off
.Lhd4:
	s_mov_b32 m0, s48
	s_nop 0
	s_cmp_eq_u32 s98, 2
	s_cbranch_scc1 .Lhd5
	global_load_lds_dwordx4 v[238:239], off
.Lhd5:
	s_waitcnt vmcnt(6)
	s_waitcnt lgkmcnt(0)
	s_barrier
	s_setprio 1
	s_waitcnt lgkmcnt(0)
	s_cmp_eq_u32 s98, 1
	s_cbranch_scc1 .Lhskip3
	v_mfma_f32_16x16x32_bf16 v[60:63], v[144:147], v[180:183], v[60:63]
	v_mfma_f32_16x16x32_bf16 v[52:55], v[152:155], v[180:183], v[52:55]
	v_mfma_f32_16x16x32_bf16 v[44:47], v[144:147], v[188:191], v[44:47]
	v_mfma_f32_16x16x32_bf16 v[36:39], v[152:155], v[188:191], v[36:39]
	v_mfma_f32_16x16x32_bf16 v[28:31], v[144:147], v[214:217], v[28:31]
	v_mfma_f32_16x16x32_bf16 v[20:23], v[152:155], v[214:217], v[20:23]
	v_mfma_f32_16x16x32_bf16 v[12:15], v[144:147], v[222:225], v[12:15]
	v_mfma_f32_16x16x32_bf16 v[4:7], v[152:155], v[222:225], v[4:7]
	v_mfma_f32_16x16x32_bf16 v[60:63], v[148:151], v[184:187], v[60:63]
	v_mfma_f32_16x16x32_bf16 v[52:55], v[160:163], v[184:187], v[52:55]
	v_mfma_f32_16x16x32_bf16 v[44:47], v[148:151], v[192:195], v[44:47]
	v_mfma_f32_16x16x32_bf16 v[36:39], v[160:163], v[192:195], v[36:39]
	v_mfma_f32_16x16x32_bf16 v[28:31], v[148:151], v[218:221], v[28:31]
	v_mfma_f32_16x16x32_bf16 v[20:23], v[160:163], v[218:221], v[20:23]
	v_mfma_f32_16x16x32_bf16 v[12:15], v[148:151], v[226:229], v[12:15]
	v_mfma_f32_16x16x32_bf16 v[4:7], v[160:163], v[226:229], v[4:7]
	s_setprio 0
	s_setprio 1
	v_mfma_f32_16x16x32_bf16 v[56:59], v[164:167], v[180:183], v[56:59]
	v_mfma_f32_16x16x32_bf16 v[48:51], v[172:175], v[180:183], v[48:51]
	v_mfma_f32_16x16x32_bf16 v[40:43], v[164:167], v[188:191], v[40:43]
	v_mfma_f32_16x16x32_bf16 v[32:35], v[172:175], v[188:191], v[32:35]
	v_mfma_f32_16x16x32_bf16 v[24:27], v[164:167], v[214:217], v[24:27]
	v_mfma_f32_16x16x32_bf16 v[16:19], v[172:175], v[214:217], v[16:19]
	v_mfma_f32_16x16x32_bf16 v[8:11], v[164:167], v[222:225], v[8:11]
	v_mfma_f32_16x16x32_bf16 v[0:3], v[172:175], v[222:225], v[0:3]
	v_mfma_f32_16x16x32_bf16 v[56:59], v[168:171], v[184:187], v[56:59]
	v_mfma_f32_16x16x32_bf16 v[48:51], v[176:179], v[184:187], v[48:51]
	v_mfma_f32_16x16x32_bf16 v[40:43], v[168:171], v[192:195], v[40:43]
	v_mfma_f32_16x16x32_bf16 v[32:35], v[176:179], v[192:195], v[32:35]
	v_mfma_f32_16x16x32_bf16 v[24:27], v[168:171], v[218:221], v[24:27]
	v_mfma_f32_16x16x32_bf16 v[16:19], v[176:179], v[218:221], v[16:19]
	v_mfma_f32_16x16x32_bf16 v[8:11], v[168:171], v[226:229], v[8:11]
	v_mfma_f32_16x16x32_bf16 v[0:3], v[176:179], v[226:229], v[0:3]
.Lhskip3:
	s_setprio 0
	s_barrier
	s_add_i32 s63, 0, 0x18000
	v_add_u32_e32 v159, s63, v141
	s_add_i32 s64, 0, 0x1c000
	ds_read_b128 v[144:147], v159
	ds_read_b128 v[148:151], v159 offset:1024
	ds_read_b128 v[152:155], v159 offset:2048
	ds_read_b128 v[160:163], v159 offset:3072
	v_add_u32_e32 v159, s64, v141
	ds_read_b128 v[164:167], v159
	ds_read_b128 v[168:171], v159 offset:1024
	ds_read_b128 v[172:175], v159 offset:2048
	ds_read_b128 v[176:179], v159 offset:3072
	s_add_u32 s30, s30, s14
	s_addc_u32 s31, s31, s15
	s_mov_b32 m0, s49
	v_lshl_add_u64 v[240:241], s[30:31], 0, v[130:131]
	s_cmp_eq_u32 s98, 2
	s_cbranch_scc1 .Lhr6
	ds_read_b128 v[180:183], v143 offset:32768
	ds_read_b128 v[184:187], v143 offset:33792
	ds_read_b128 v[188:191], v143 offset:34816
	ds_read_b128 v[192:195], v143 offset:35840
	ds_read_b128 v[214:217], v143 offset:36864
	ds_read_b128 v[218:221], v143 offset:37888
	ds_read_b128 v[222:225], v143 offset:38912
	ds_read_b128 v[226:229], v143 offset:39936
.Lhr6:
	s_cmp_eq_u32 s98, 1
	s_cbranch_scc1 .Lhd7
	global_load_lds_dwordx4 v[240:241], off
.Lhd7:
	v_lshl_add_u64 v[240:241], s[30:31], 0, v[132:133]
	s_mov_b32 m0, s50
	s_nop 0
	s_cmp_eq_u32 s98, 1
	s_cbranch_scc1 .Lhd8
	global_load_lds_dwordx4 v[240:241], off

.Lhskip5:
	s_setprio 0
	s_barrier
	s_add_i32 s30, s63, s44
	v_lshl_add_u64 v[156:157], v[156:157], 0, s[80:81]
	s_mov_b32 m0, s30
	s_cmp_eq_u32 s98, 1
	s_cbranch_scc1 .Lhr9
	ds_read_b128 v[180:183], v143 offset:49152
	ds_read_b128 v[184:187], v143 offset:50176
	ds_read_b128 v[188:191], v143 offset:51200
	ds_read_b128 v[192:195], v143 offset:52224
	ds_read_b128 v[214:217], v143 offset:53248
	ds_read_b128 v[218:221], v143 offset:54272
	ds_read_b128 v[222:225], v143 offset:55296
	ds_read_b128 v[226:229], v143 offset:56320
.Lhr9:
	global_load_lds_dwordx4 v[156:157], off
	v_lshl_add_u64 v[156:157], v[230:231], 0, s[80:81]
	s_add_i32 m0, s30, 0x2000
	s_add_i32 s30, s64, s44
	global_load_lds_dwordx4 v[156:157], off
	v_lshl_add_u64 v[156:157], v[232:233], 0, s[80:81]
	s_mov_b32 m0, s30
	s_nop 0
	global_load_lds_dwordx4 v[156:157], off
	v_lshl_add_u64 v[156:157], v[234:235], 0, s[80:81]
	s_add_i32 m0, s30, 0x2000
	s_nop 0
	global_load_lds_dwordx4 v[156:157], off
	v_lshl_add_u64 v[156:157], v[236:237], 0, s[80:81]
	s_mov_b32 m0, s51
	s_nop 0
	s_cmp_eq_u32 s98, 2
	s_cbranch_scc1 .Lhd10
	global_load_lds_dwordx4 v[156:157], off
.Lhd10:
	v_lshl_add_u64 v[156:157], v[238:239], 0, s[80:81]
	s_mov_b32 m0, s52
	s_nop 0
	s_cmp_eq_u32 s98, 2
	s_cbranch_scc1 .Lhd11
	global_load_lds_dwordx4 v[156:157], off
